# phase 3 (attention + DeltaNet items): static s_setprio 1 for waves 4-7, reset at phase end (timing only)
# speedup vs baseline: 1.0013x; 1.0013x over previous
.LBB0_624:
	v_readfirstlane_b32 s98, v224
	s_nop 3
	s_cmp_lt_u32 s98, 0x100
	s_cbranch_scc1 .Lmy_p3_noprio
	s_setprio 1

.LBB0_798:
	s_setprio 0
	s_cmp_lt_i32 s30, 5
	s_cselect_b64 s[2:3], -1, 0
	s_cmp_gt_i32 s31, 4
	s_cselect_b64 s[0:1], -1, 0
	s_and_b64 s[0:1], s[2:3], s[0:1]
	s_waitcnt lgkmcnt(0)
	v_readlane_b32 s72, v255, 38
	s_andn2_b64 vcc, exec, s[0:1]
	v_readlane_b32 s73, v255, 39
	v_readlane_b32 s74, v255, 40
	v_readlane_b32 s75, v255, 41
	v_readlane_b32 s76, v255, 42
	v_readlane_b32 s77, v255, 43
	v_readlane_b32 s78, v255, 44
	v_readlane_b32 s79, v255, 45
	s_cbranch_vccnz .LBB0_856
	s_andn2_b64 vcc, exec, s[46:47]
	s_cbranch_vccnz .LBB0_853
	s_waitcnt vmcnt(0)
	s_barrier
	s_mov_b64 s[0:1], exec
	v_readlane_b32 s4, v255, 0
	v_readlane_b32 s5, v255, 1
	s_and_b64 s[4:5], s[0:1], s[4:5]
	s_mov_b64 exec, s[4:5]
	s_cbranch_execz .LBB0_852
	s_waitcnt vmcnt(0)
	v_mov_b32_e32 v0, 0
	s_waitcnt vmcnt(0) expcnt(0) lgkmcnt(0)
	ds_read_b32 v2, v0
	ds_read_b32 v1, v0 offset:4
	s_waitcnt lgkmcnt(1)
	v_cmp_ne_u32_e32 vcc, 0, v2
	s_cbranch_vccnz .LBB0_816
	v_readlane_b32 s4, v255, 2
	s_mul_i32 s33, s85, s4
	s_add_u32 s4, s28, 0x163fc300
	s_addc_u32 s5, s29, 0
	s_add_u32 s6, s28, 0x163fc500
	s_addc_u32 s7, s29, 0
	s_add_u32 s8, s28, 0x163fc600
	s_addc_u32 s9, s29, 0
	s_add_u32 s10, s28, 0x163fc700
	s_addc_u32 s11, s29, 0
	s_add_u32 s12, s28, 0x163fc800
	s_addc_u32 s13, s29, 0
	s_add_u32 s14, s28, 0x163fc900
	s_addc_u32 s15, s29, 0
	s_add_u32 s16, s28, 0x163fca00
	s_addc_u32 s17, s29, 0
	s_add_u32 s18, s28, 0x163fcb00
	s_addc_u32 s19, s29, 0
	s_add_u32 s20, s28, 0x163fcc00
	s_addc_u32 s21, s29, 0
	s_add_u32 s22, s28, 0x163fcd00
	s_addc_u32 s23, s29, 0
	s_add_u32 s24, s28, 0x163fce00
	s_addc_u32 s25, s29, 0
	s_add_u32 s26, s28, 0x163fcf00
	s_addc_u32 s27, s29, 0
	s_add_u32 s34, s28, 0x163fd000
	s_addc_u32 s35, s29, 0
	s_add_u32 s36, s28, 0x163fd100
	s_addc_u32 s37, s29, 0
	s_add_u32 s38, s28, 0x163fd200
	s_addc_u32 s39, s29, 0
	s_add_u32 s40, s28, 0x163fd300
	s_addc_u32 s41, s29, 0
	s_add_u32 s44, s28, 0x163fd400
	s_mul_i32 s33, s33, s84
	s_addc_u32 s45, s29, 0
	s_mov_b32 s42, 1
	s_branch .LBB0_804
